# LDS-DMA attention loop: M0 written ahead of the preceding MFMA so each DMA load needs no wait-state s_nop (8 fewer s_nop per tile)
# speedup vs baseline: 1.0050x; 1.0015x over previous
.Lattn_nf_loop:
	ds_read_b128 v[98:101], v82 offset:0
	ds_read_b128 v[102:105], v83 offset:0
	ds_read_b128 v[106:109], v84 offset:0
	ds_read_b128 v[110:113], v85 offset:0
	s_and_b32 s10, s15, 1
	s_xor_b32 s10, s10, 1
	s_lshl_b32 s10, s10, 15
	s_add_i32 s10, s10, s11
	s_add_i32 s6, s10, 0x10000
	s_add_i32 m0, s10, 0x0
	s_waitcnt lgkmcnt(3)
	v_mfma_f32_32x32x16_bf16 v[138:153], v[98:101], v[10:13], 0
	ds_read_b128 v[98:101], v82 offset:8192
	global_load_lds_dwordx4 v124, s[64:65]
	s_add_i32 m0, s10, 0x2000
	s_waitcnt lgkmcnt(3)
	v_mfma_f32_32x32x16_bf16 v[138:153], v[102:105], v[14:17], v[138:153]
	ds_read_b128 v[102:105], v83 offset:8192
	global_load_lds_dwordx4 v124, s[66:67]
	s_add_i32 m0, s10, 0x4000
	s_waitcnt lgkmcnt(3)
	v_mfma_f32_32x32x16_bf16 v[138:153], v[106:109], v[2:5], v[138:153]
	ds_read_b128 v[106:109], v84 offset:8192
	global_load_lds_dwordx4 v124, s[68:69]
	s_add_i32 m0, s10, 0x6000
	s_waitcnt lgkmcnt(3)
	v_mfma_f32_32x32x16_bf16 v[138:153], v[110:113], v[6:9], v[138:153]
	ds_read_b128 v[110:113], v85 offset:8192
	global_load_lds_dwordx4 v124, s[70:71]
	v_add_u32_e32 v124, s36, v124
	s_add_i32 m0, s6, 0x0
	s_waitcnt lgkmcnt(3)
	v_mfma_f32_32x32x16_bf16 v[154:169], v[98:101], v[10:13], 0
	ds_read_b128 v[98:101], v82 offset:16384
	global_load_lds_dwordx4 v125, s[72:73]
	ds_read_b128 v[128:131], v86 offset:0
	ds_read_b128 v[184:187], v86 offset:8192
	s_nop 1
	v_exp_f32_e32 v138, v138
	v_exp_f32_e32 v139, v139
	v_exp_f32_e32 v140, v140
	v_exp_f32_e32 v141, v141
	v_exp_f32_e32 v142, v142
	v_exp_f32_e32 v143, v143
	s_add_i32 m0, s6, 0x2000
	s_waitcnt lgkmcnt(5)
	v_mfma_f32_32x32x16_bf16 v[154:169], v[102:105], v[14:17], v[154:169]
	ds_read_b128 v[102:105], v83 offset:16384
	global_load_lds_dwordx4 v125, s[74:75]
	ds_read_b128 v[188:191], v86 offset:16384
	ds_read_b128 v[192:195], v86 offset:24576
	v_exp_f32_e32 v144, v144
	v_exp_f32_e32 v145, v145
	v_add_f32_e32 v122, v138, v122
	v_add_f32_e32 v122, v139, v122
	v_add_f32_e32 v122, v140, v122
	v_add_f32_e32 v122, v141, v122
	v_add_f32_e32 v122, v142, v122
	v_add_f32_e32 v122, v143, v122
	v_add_f32_e32 v122, v144, v122
	v_add_f32_e32 v122, v145, v122
	v_cvt_pk_bf16_f32 v114, v138, v139
	v_cvt_pk_bf16_f32 v115, v140, v141
	v_cvt_pk_bf16_f32 v116, v142, v143
	v_cvt_pk_bf16_f32 v117, v144, v145
	s_add_i32 m0, s6, 0x4000
	s_waitcnt lgkmcnt(7)
	v_mfma_f32_32x32x16_bf16 v[154:169], v[106:109], v[2:5], v[154:169]
	ds_read_b128 v[106:109], v84 offset:16384
	global_load_lds_dwordx4 v125, s[76:77]
	ds_read_b128 v[196:199], v87 offset:0
	v_exp_f32_e32 v146, v146
	v_exp_f32_e32 v147, v147
	s_add_i32 m0, s6, 0x6000
	s_waitcnt lgkmcnt(8)
	v_mfma_f32_32x32x16_bf16 v[154:169], v[110:113], v[6:9], v[154:169]
	ds_read_b128 v[110:113], v85 offset:16384
	global_load_lds_dwordx4 v125, s[78:79]
	v_add_u32_e32 v125, s38, v125
	ds_read_b128 v[216:219], v87 offset:8192
	v_exp_f32_e32 v148, v148
	v_exp_f32_e32 v149, v149
	s_waitcnt lgkmcnt(8)
	v_mfma_f32_32x32x16_bf16 v[18:33], v[128:131], v[114:117], v[18:33]
	v_exp_f32_e32 v150, v150
	v_exp_f32_e32 v151, v151
	s_waitcnt lgkmcnt(7)
	v_mfma_f32_32x32x16_bf16 v[34:49], v[184:187], v[114:117], v[34:49]
	ds_read_b128 v[200:203], v87 offset:16384
	v_exp_f32_e32 v152, v152
	v_exp_f32_e32 v153, v153
	s_waitcnt lgkmcnt(6)
	v_mfma_f32_32x32x16_bf16 v[50:65], v[188:191], v[114:117], v[50:65]
	ds_read_b128 v[204:207], v87 offset:24576
	v_add_f32_e32 v122, v146, v122
	v_add_f32_e32 v122, v147, v122
	v_add_f32_e32 v122, v148, v122
	v_add_f32_e32 v122, v149, v122
	s_waitcnt lgkmcnt(6)
	v_mfma_f32_32x32x16_bf16 v[66:81], v[192:195], v[114:117], v[66:81]
	v_add_f32_e32 v122, v150, v122
	v_add_f32_e32 v122, v151, v122
	v_add_f32_e32 v122, v152, v122
	v_add_f32_e32 v122, v153, v122
	v_cvt_pk_bf16_f32 v118, v146, v147
	v_cvt_pk_bf16_f32 v119, v148, v149
	v_cvt_pk_bf16_f32 v120, v150, v151
	v_cvt_pk_bf16_f32 v121, v152, v153
	v_mfma_f32_32x32x16_bf16 v[138:153], v[98:101], v[10:13], 0
	ds_read_b128 v[98:101], v82 offset:24576
	ds_read_b128 v[128:131], v88 offset:0
	v_exp_f32_e32 v154, v154
	v_exp_f32_e32 v155, v155
	v_mfma_f32_32x32x16_bf16 v[138:153], v[102:105], v[14:17], v[138:153]
	ds_read_b128 v[102:105], v83 offset:24576
	ds_read_b128 v[184:187], v88 offset:8192
	v_exp_f32_e32 v156, v156
	v_exp_f32_e32 v157, v157
	s_waitcnt lgkmcnt(8)
	v_mfma_f32_32x32x16_bf16 v[18:33], v[196:199], v[118:121], v[18:33]
	v_exp_f32_e32 v158, v158
	v_exp_f32_e32 v159, v159
	s_waitcnt lgkmcnt(6)
	v_mfma_f32_32x32x16_bf16 v[34:49], v[216:219], v[118:121], v[34:49]
	ds_read_b128 v[188:191], v88 offset:16384
	v_exp_f32_e32 v160, v160
	v_exp_f32_e32 v161, v161
	s_waitcnt lgkmcnt(6)
	v_mfma_f32_32x32x16_bf16 v[50:65], v[200:203], v[118:121], v[50:65]
	ds_read_b128 v[192:195], v88 offset:24576
	v_add_f32_e32 v122, v154, v122
	v_add_f32_e32 v122, v155, v122
	v_add_f32_e32 v122, v156, v122
	v_add_f32_e32 v122, v157, v122
	s_waitcnt lgkmcnt(6)
	v_mfma_f32_32x32x16_bf16 v[66:81], v[204:207], v[118:121], v[66:81]
	v_add_f32_e32 v122, v158, v122
	v_add_f32_e32 v122, v159, v122
	v_add_f32_e32 v122, v160, v122
	v_add_f32_e32 v122, v161, v122
	v_cvt_pk_bf16_f32 v114, v154, v155
	v_cvt_pk_bf16_f32 v115, v156, v157
	v_cvt_pk_bf16_f32 v116, v158, v159
	v_cvt_pk_bf16_f32 v117, v160, v161
	v_mfma_f32_32x32x16_bf16 v[138:153], v[106:109], v[2:5], v[138:153]
	ds_read_b128 v[106:109], v84 offset:24576
	ds_read_b128 v[196:199], v89 offset:0
	v_exp_f32_e32 v162, v162
	v_exp_f32_e32 v163, v163
	v_mfma_f32_32x32x16_bf16 v[138:153], v[110:113], v[6:9], v[138:153]
	ds_read_b128 v[110:113], v85 offset:24576
	ds_read_b128 v[216:219], v89 offset:8192
	v_exp_f32_e32 v164, v164
	v_exp_f32_e32 v165, v165
	s_waitcnt lgkmcnt(8)
	v_mfma_f32_32x32x16_bf16 v[18:33], v[128:131], v[114:117], v[18:33]
	v_exp_f32_e32 v166, v166
	v_exp_f32_e32 v167, v167
	s_waitcnt lgkmcnt(6)
	v_mfma_f32_32x32x16_bf16 v[34:49], v[184:187], v[114:117], v[34:49]
	ds_read_b128 v[200:203], v89 offset:16384
	v_exp_f32_e32 v168, v168
	v_exp_f32_e32 v169, v169
	s_waitcnt lgkmcnt(6)
	v_mfma_f32_32x32x16_bf16 v[50:65], v[188:191], v[114:117], v[50:65]
	ds_read_b128 v[204:207], v89 offset:24576
	v_add_f32_e32 v122, v162, v122
	v_add_f32_e32 v122, v163, v122
	v_add_f32_e32 v122, v164, v122
	v_add_f32_e32 v122, v165, v122
	s_waitcnt lgkmcnt(6)
	v_mfma_f32_32x32x16_bf16 v[66:81], v[192:195], v[114:117], v[66:81]
	v_add_f32_e32 v122, v166, v122
	v_add_f32_e32 v122, v167, v122
	v_add_f32_e32 v122, v168, v122
	v_add_f32_e32 v122, v169, v122
	v_cvt_pk_bf16_f32 v118, v162, v163
	v_cvt_pk_bf16_f32 v119, v164, v165
	v_cvt_pk_bf16_f32 v120, v166, v167
	v_cvt_pk_bf16_f32 v121, v168, v169
	v_mfma_f32_32x32x16_bf16 v[154:169], v[98:101], v[10:13], 0
	ds_read_b128 v[128:131], v90 offset:0
	v_exp_f32_e32 v138, v138
	v_exp_f32_e32 v139, v139
	v_mfma_f32_32x32x16_bf16 v[154:169], v[102:105], v[14:17], v[154:169]
	ds_read_b128 v[184:187], v90 offset:8192
	v_exp_f32_e32 v140, v140
	v_exp_f32_e32 v141, v141
	s_waitcnt lgkmcnt(6)
	v_mfma_f32_32x32x16_bf16 v[18:33], v[196:199], v[118:121], v[18:33]
	v_exp_f32_e32 v142, v142
	v_exp_f32_e32 v143, v143
	s_waitcnt lgkmcnt(4)
	v_mfma_f32_32x32x16_bf16 v[34:49], v[216:219], v[118:121], v[34:49]
	ds_read_b128 v[188:191], v90 offset:16384
	v_exp_f32_e32 v144, v144
	v_exp_f32_e32 v145, v145
	s_waitcnt lgkmcnt(4)
	v_mfma_f32_32x32x16_bf16 v[50:65], v[200:203], v[118:121], v[50:65]
	ds_read_b128 v[192:195], v90 offset:24576
	v_add_f32_e32 v122, v138, v122
	v_add_f32_e32 v122, v139, v122
	v_add_f32_e32 v122, v140, v122
	v_add_f32_e32 v122, v141, v122
	s_waitcnt lgkmcnt(4)
	v_mfma_f32_32x32x16_bf16 v[66:81], v[204:207], v[118:121], v[66:81]
	v_add_f32_e32 v122, v142, v122
	v_add_f32_e32 v122, v143, v122
	v_add_f32_e32 v122, v144, v122
	v_add_f32_e32 v122, v145, v122
	v_cvt_pk_bf16_f32 v114, v138, v139
	v_cvt_pk_bf16_f32 v115, v140, v141
	v_cvt_pk_bf16_f32 v116, v142, v143
	v_cvt_pk_bf16_f32 v117, v144, v145
	v_mfma_f32_32x32x16_bf16 v[154:169], v[106:109], v[2:5], v[154:169]
	ds_read_b128 v[196:199], v91 offset:0
	v_exp_f32_e32 v146, v146
	v_exp_f32_e32 v147, v147
	v_mfma_f32_32x32x16_bf16 v[154:169], v[110:113], v[6:9], v[154:169]
	ds_read_b128 v[216:219], v91 offset:8192
	v_exp_f32_e32 v148, v148
	v_exp_f32_e32 v149, v149
	s_waitcnt lgkmcnt(5)
	v_mfma_f32_32x32x16_bf16 v[18:33], v[128:131], v[114:117], v[18:33]
	v_exp_f32_e32 v150, v150
	v_exp_f32_e32 v151, v151
	s_waitcnt lgkmcnt(4)
	v_mfma_f32_32x32x16_bf16 v[34:49], v[184:187], v[114:117], v[34:49]
	ds_read_b128 v[200:203], v91 offset:16384
	v_exp_f32_e32 v152, v152
	v_exp_f32_e32 v153, v153
	s_waitcnt lgkmcnt(4)
	v_mfma_f32_32x32x16_bf16 v[50:65], v[188:191], v[114:117], v[50:65]
	ds_read_b128 v[204:207], v91 offset:24576
	v_add_f32_e32 v122, v146, v122
	v_add_f32_e32 v122, v147, v122
	v_add_f32_e32 v122, v148, v122
	v_add_f32_e32 v122, v149, v122
	s_waitcnt lgkmcnt(4)
	v_mfma_f32_32x32x16_bf16 v[66:81], v[192:195], v[114:117], v[66:81]
	v_add_f32_e32 v122, v150, v122
	v_add_f32_e32 v122, v151, v122
	v_add_f32_e32 v122, v152, v122
	v_add_f32_e32 v122, v153, v122
	v_cvt_pk_bf16_f32 v118, v146, v147
	v_cvt_pk_bf16_f32 v119, v148, v149
	v_cvt_pk_bf16_f32 v120, v150, v151
	v_cvt_pk_bf16_f32 v121, v152, v153
	s_waitcnt lgkmcnt(3)
	s_nop 0
	v_mfma_f32_32x32x16_bf16 v[18:33], v[196:199], v[118:121], v[18:33]
	ds_read_b128 v[128:131], v92 offset:0
	v_exp_f32_e32 v154, v154
	v_exp_f32_e32 v155, v155
	v_exp_f32_e32 v156, v156
	s_waitcnt lgkmcnt(3)
	v_mfma_f32_32x32x16_bf16 v[34:49], v[216:219], v[118:121], v[34:49]
	ds_read_b128 v[184:187], v92 offset:8192
	v_exp_f32_e32 v157, v157
	v_exp_f32_e32 v158, v158
	v_exp_f32_e32 v159, v159
	v_exp_f32_e32 v160, v160
	s_waitcnt lgkmcnt(3)
	v_mfma_f32_32x32x16_bf16 v[50:65], v[200:203], v[118:121], v[50:65]
	ds_read_b128 v[188:191], v92 offset:16384
	v_exp_f32_e32 v161, v161
	v_add_f32_e32 v122, v154, v122
	v_add_f32_e32 v122, v155, v122
	v_add_f32_e32 v122, v156, v122
	v_add_f32_e32 v122, v157, v122
	v_add_f32_e32 v122, v158, v122
	s_waitcnt lgkmcnt(3)
	v_mfma_f32_32x32x16_bf16 v[66:81], v[204:207], v[118:121], v[66:81]
	ds_read_b128 v[192:195], v92 offset:24576
	v_add_f32_e32 v122, v159, v122
	v_add_f32_e32 v122, v160, v122
	v_add_f32_e32 v122, v161, v122
	v_xor_b32_e32 v82, 0x8000, v82
	v_xor_b32_e32 v83, 0x8000, v83
	v_xor_b32_e32 v84, 0x8000, v84
	v_xor_b32_e32 v85, 0x8000, v85
	v_cvt_pk_bf16_f32 v114, v154, v155
	v_cvt_pk_bf16_f32 v115, v156, v157
	v_cvt_pk_bf16_f32 v116, v158, v159
	v_cvt_pk_bf16_f32 v117, v160, v161
	s_waitcnt lgkmcnt(3)
	s_nop 0
	v_mfma_f32_32x32x16_bf16 v[18:33], v[128:131], v[114:117], v[18:33]
	ds_read_b128 v[196:199], v93 offset:0
	v_exp_f32_e32 v162, v162
	v_exp_f32_e32 v163, v163
	v_exp_f32_e32 v164, v164
	s_waitcnt lgkmcnt(3)
	v_mfma_f32_32x32x16_bf16 v[34:49], v[184:187], v[114:117], v[34:49]
	ds_read_b128 v[216:219], v93 offset:8192
	v_exp_f32_e32 v165, v165
	v_exp_f32_e32 v166, v166
	v_exp_f32_e32 v167, v167
	s_waitcnt lgkmcnt(3)
	v_mfma_f32_32x32x16_bf16 v[50:65], v[188:191], v[114:117], v[50:65]
	ds_read_b128 v[200:203], v93 offset:16384
	v_exp_f32_e32 v168, v168
	v_exp_f32_e32 v169, v169
	v_add_f32_e32 v122, v162, v122
	v_add_f32_e32 v122, v163, v122
	s_waitcnt lgkmcnt(3)
	v_mfma_f32_32x32x16_bf16 v[66:81], v[192:195], v[114:117], v[66:81]
	ds_read_b128 v[204:207], v93 offset:24576
	v_add_f32_e32 v122, v164, v122
	v_add_f32_e32 v122, v165, v122
	v_add_f32_e32 v122, v166, v122
	v_add_f32_e32 v122, v167, v122
	v_add_f32_e32 v122, v168, v122
	v_add_f32_e32 v122, v169, v122
	v_cvt_pk_bf16_f32 v118, v162, v163
	v_cvt_pk_bf16_f32 v119, v164, v165
	v_cvt_pk_bf16_f32 v120, v166, v167
	v_cvt_pk_bf16_f32 v121, v168, v169
	s_waitcnt lgkmcnt(3)
	s_nop 0
	v_mfma_f32_32x32x16_bf16 v[18:33], v[196:199], v[118:121], v[18:33]
	v_xor_b32_e32 v86, 0x8000, v86
	v_xor_b32_e32 v87, 0x8000, v87
	s_waitcnt lgkmcnt(2)
	v_mfma_f32_32x32x16_bf16 v[34:49], v[216:219], v[118:121], v[34:49]
	v_xor_b32_e32 v88, 0x8000, v88
	v_xor_b32_e32 v89, 0x8000, v89
	s_waitcnt lgkmcnt(1)
	v_mfma_f32_32x32x16_bf16 v[50:65], v[200:203], v[118:121], v[50:65]
	v_xor_b32_e32 v90, 0x8000, v90
	v_xor_b32_e32 v91, 0x8000, v91
	s_waitcnt lgkmcnt(0)
	v_mfma_f32_32x32x16_bf16 v[66:81], v[204:207], v[118:121], v[66:81]
	v_xor_b32_e32 v92, 0x8000, v92
	v_xor_b32_e32 v93, 0x8000, v93
	s_waitcnt vmcnt(0)
	s_waitcnt lgkmcnt(0)
	s_barrier
	s_add_i32 s15, s15, 1
	s_cmp_eq_u32 s15, 33
	s_cbranch_scc0 .Lattn_nf_loop
	ds_read_b128 v[98:101], v82 offset:0
	ds_read_b128 v[102:105], v83 offset:0
	ds_read_b128 v[106:109], v84 offset:0
	ds_read_b128 v[110:113], v85 offset:0
	s_waitcnt lgkmcnt(3)
	v_mfma_f32_32x32x16_bf16 v[138:153], v[98:101], v[10:13], 0
	ds_read_b128 v[98:101], v82 offset:8192
	s_waitcnt lgkmcnt(3)
	v_mfma_f32_32x32x16_bf16 v[138:153], v[102:105], v[14:17], v[138:153]
	ds_read_b128 v[102:105], v83 offset:8192
	s_waitcnt lgkmcnt(3)
	v_mfma_f32_32x32x16_bf16 v[138:153], v[106:109], v[2:5], v[138:153]
	ds_read_b128 v[106:109], v84 offset:8192
	s_waitcnt lgkmcnt(3)
	v_mfma_f32_32x32x16_bf16 v[138:153], v[110:113], v[6:9], v[138:153]
	ds_read_b128 v[110:113], v85 offset:8192
	s_waitcnt lgkmcnt(3)
	v_mfma_f32_32x32x16_bf16 v[154:169], v[98:101], v[10:13], 0
	ds_read_b128 v[98:101], v82 offset:16384
	ds_read_b128 v[128:131], v86 offset:0
	ds_read_b128 v[184:187], v86 offset:8192
	s_nop 5
	v_exp_f32_e32 v138, v138
	v_exp_f32_e32 v139, v139
	v_exp_f32_e32 v140, v140
	v_exp_f32_e32 v141, v141
	v_exp_f32_e32 v142, v142
	v_exp_f32_e32 v143, v143
	s_waitcnt lgkmcnt(5)
	v_mfma_f32_32x32x16_bf16 v[154:169], v[102:105], v[14:17], v[154:169]
	ds_read_b128 v[102:105], v83 offset:16384
	ds_read_b128 v[188:191], v86 offset:16384
	ds_read_b128 v[192:195], v86 offset:24576
	v_exp_f32_e32 v144, v144
	v_exp_f32_e32 v145, v145
	v_add_f32_e32 v122, v138, v122
	v_add_f32_e32 v122, v139, v122
	v_add_f32_e32 v122, v140, v122
	v_add_f32_e32 v122, v141, v122
	v_add_f32_e32 v122, v142, v122
	v_add_f32_e32 v122, v143, v122
	v_add_f32_e32 v122, v144, v122
	v_add_f32_e32 v122, v145, v122
	v_cvt_pk_bf16_f32 v114, v138, v139
	v_cvt_pk_bf16_f32 v115, v140, v141
	v_cvt_pk_bf16_f32 v116, v142, v143
	v_cvt_pk_bf16_f32 v117, v144, v145
	s_waitcnt lgkmcnt(7)
	v_mfma_f32_32x32x16_bf16 v[154:169], v[106:109], v[2:5], v[154:169]
	ds_read_b128 v[106:109], v84 offset:16384
	ds_read_b128 v[196:199], v87 offset:0
	v_exp_f32_e32 v146, v146
	v_exp_f32_e32 v147, v147
	s_waitcnt lgkmcnt(8)
	v_mfma_f32_32x32x16_bf16 v[154:169], v[110:113], v[6:9], v[154:169]
	ds_read_b128 v[110:113], v85 offset:16384
	ds_read_b128 v[216:219], v87 offset:8192
	v_exp_f32_e32 v148, v148
	v_exp_f32_e32 v149, v149
	s_waitcnt lgkmcnt(8)
	v_mfma_f32_32x32x16_bf16 v[18:33], v[128:131], v[114:117], v[18:33]
	v_exp_f32_e32 v150, v150
	v_exp_f32_e32 v151, v151
	s_waitcnt lgkmcnt(7)
	v_mfma_f32_32x32x16_bf16 v[34:49], v[184:187], v[114:117], v[34:49]
	ds_read_b128 v[200:203], v87 offset:16384
	v_exp_f32_e32 v152, v152
	v_exp_f32_e32 v153, v153
	s_waitcnt lgkmcnt(6)
	v_mfma_f32_32x32x16_bf16 v[50:65], v[188:191], v[114:117], v[50:65]
	ds_read_b128 v[204:207], v87 offset:24576
	v_add_f32_e32 v122, v146, v122
	v_add_f32_e32 v122, v147, v122
	v_add_f32_e32 v122, v148, v122
	v_add_f32_e32 v122, v149, v122
	s_waitcnt lgkmcnt(6)
	v_mfma_f32_32x32x16_bf16 v[66:81], v[192:195], v[114:117], v[66:81]
	v_add_f32_e32 v122, v150, v122
	v_add_f32_e32 v122, v151, v122
	v_add_f32_e32 v122, v152, v122
	v_add_f32_e32 v122, v153, v122
	v_cvt_pk_bf16_f32 v118, v146, v147
	v_cvt_pk_bf16_f32 v119, v148, v149
	v_cvt_pk_bf16_f32 v120, v150, v151
	v_cvt_pk_bf16_f32 v121, v152, v153
	v_mfma_f32_32x32x16_bf16 v[138:153], v[98:101], v[10:13], 0
	ds_read_b128 v[98:101], v82 offset:24576
	ds_read_b128 v[128:131], v88 offset:0
	v_exp_f32_e32 v154, v154
	v_exp_f32_e32 v155, v155
	v_mfma_f32_32x32x16_bf16 v[138:153], v[102:105], v[14:17], v[138:153]
	ds_read_b128 v[102:105], v83 offset:24576
	ds_read_b128 v[184:187], v88 offset:8192
	v_exp_f32_e32 v156, v156
	v_exp_f32_e32 v157, v157
	s_waitcnt lgkmcnt(8)
	v_mfma_f32_32x32x16_bf16 v[18:33], v[196:199], v[118:121], v[18:33]
	v_exp_f32_e32 v158, v158
	v_exp_f32_e32 v159, v159
	s_waitcnt lgkmcnt(6)
	v_mfma_f32_32x32x16_bf16 v[34:49], v[216:219], v[118:121], v[34:49]
	ds_read_b128 v[188:191], v88 offset:16384
	v_exp_f32_e32 v160, v160
	v_exp_f32_e32 v161, v161
	s_waitcnt lgkmcnt(6)
	v_mfma_f32_32x32x16_bf16 v[50:65], v[200:203], v[118:121], v[50:65]
	ds_read_b128 v[192:195], v88 offset:24576
	v_add_f32_e32 v122, v154, v122
	v_add_f32_e32 v122, v155, v122
	v_add_f32_e32 v122, v156, v122
	v_add_f32_e32 v122, v157, v122
	s_waitcnt lgkmcnt(6)
	v_mfma_f32_32x32x16_bf16 v[66:81], v[204:207], v[118:121], v[66:81]
	v_add_f32_e32 v122, v158, v122
	v_add_f32_e32 v122, v159, v122
	v_add_f32_e32 v122, v160, v122
	v_add_f32_e32 v122, v161, v122
	v_cvt_pk_bf16_f32 v114, v154, v155
	v_cvt_pk_bf16_f32 v115, v156, v157
	v_cvt_pk_bf16_f32 v116, v158, v159
	v_cvt_pk_bf16_f32 v117, v160, v161
	v_mfma_f32_32x32x16_bf16 v[138:153], v[106:109], v[2:5], v[138:153]
	ds_read_b128 v[106:109], v84 offset:24576
	ds_read_b128 v[196:199], v89 offset:0
	v_exp_f32_e32 v162, v162
	v_exp_f32_e32 v163, v163
	v_mfma_f32_32x32x16_bf16 v[138:153], v[110:113], v[6:9], v[138:153]
	ds_read_b128 v[110:113], v85 offset:24576
	ds_read_b128 v[216:219], v89 offset:8192
	v_exp_f32_e32 v164, v164
	v_exp_f32_e32 v165, v165
	s_waitcnt lgkmcnt(8)
	v_mfma_f32_32x32x16_bf16 v[18:33], v[128:131], v[114:117], v[18:33]
	v_exp_f32_e32 v166, v166
	v_exp_f32_e32 v167, v167
	s_waitcnt lgkmcnt(6)
	v_mfma_f32_32x32x16_bf16 v[34:49], v[184:187], v[114:117], v[34:49]
	ds_read_b128 v[200:203], v89 offset:16384
	v_exp_f32_e32 v168, v168
	v_exp_f32_e32 v169, v169
	s_waitcnt lgkmcnt(6)
	v_mfma_f32_32x32x16_bf16 v[50:65], v[188:191], v[114:117], v[50:65]
	ds_read_b128 v[204:207], v89 offset:24576
	v_add_f32_e32 v122, v162, v122
	v_add_f32_e32 v122, v163, v122
	v_add_f32_e32 v122, v164, v122
	v_add_f32_e32 v122, v165, v122
	s_waitcnt lgkmcnt(6)
	v_mfma_f32_32x32x16_bf16 v[66:81], v[192:195], v[114:117], v[66:81]
	v_add_f32_e32 v122, v166, v122
	v_add_f32_e32 v122, v167, v122
	v_add_f32_e32 v122, v168, v122
	v_add_f32_e32 v122, v169, v122
	v_cvt_pk_bf16_f32 v118, v162, v163
	v_cvt_pk_bf16_f32 v119, v164, v165
	v_cvt_pk_bf16_f32 v120, v166, v167
	v_cvt_pk_bf16_f32 v121, v168, v169
	v_mfma_f32_32x32x16_bf16 v[154:169], v[98:101], v[10:13], 0
	ds_read_b128 v[128:131], v90 offset:0
	v_exp_f32_e32 v138, v138
	v_exp_f32_e32 v139, v139
	v_mfma_f32_32x32x16_bf16 v[154:169], v[102:105], v[14:17], v[154:169]
	ds_read_b128 v[184:187], v90 offset:8192
	v_exp_f32_e32 v140, v140
	v_exp_f32_e32 v141, v141
	s_waitcnt lgkmcnt(6)
	v_mfma_f32_32x32x16_bf16 v[18:33], v[196:199], v[118:121], v[18:33]
	v_exp_f32_e32 v142, v142
	v_exp_f32_e32 v143, v143
	s_waitcnt lgkmcnt(4)
	v_mfma_f32_32x32x16_bf16 v[34:49], v[216:219], v[118:121], v[34:49]
	ds_read_b128 v[188:191], v90 offset:16384
	v_exp_f32_e32 v144, v144
	v_exp_f32_e32 v145, v145
	s_waitcnt lgkmcnt(4)
	v_mfma_f32_32x32x16_bf16 v[50:65], v[200:203], v[118:121], v[50:65]
	ds_read_b128 v[192:195], v90 offset:24576
	v_add_f32_e32 v122, v138, v122
	v_add_f32_e32 v122, v139, v122
	v_add_f32_e32 v122, v140, v122
	v_add_f32_e32 v122, v141, v122
	s_waitcnt lgkmcnt(4)
	v_mfma_f32_32x32x16_bf16 v[66:81], v[204:207], v[118:121], v[66:81]
	v_add_f32_e32 v122, v142, v122
	v_add_f32_e32 v122, v143, v122
	v_add_f32_e32 v122, v144, v122
	v_add_f32_e32 v122, v145, v122
	v_cvt_pk_bf16_f32 v114, v138, v139
	v_cvt_pk_bf16_f32 v115, v140, v141
	v_cvt_pk_bf16_f32 v116, v142, v143
	v_cvt_pk_bf16_f32 v117, v144, v145
	v_mfma_f32_32x32x16_bf16 v[154:169], v[106:109], v[2:5], v[154:169]
	ds_read_b128 v[196:199], v91 offset:0
	v_exp_f32_e32 v146, v146
	v_exp_f32_e32 v147, v147
	v_mfma_f32_32x32x16_bf16 v[154:169], v[110:113], v[6:9], v[154:169]
	ds_read_b128 v[216:219], v91 offset:8192
	v_exp_f32_e32 v148, v148
	v_exp_f32_e32 v149, v149
	s_waitcnt lgkmcnt(5)
	v_mfma_f32_32x32x16_bf16 v[18:33], v[128:131], v[114:117], v[18:33]
	v_exp_f32_e32 v150, v150
	v_exp_f32_e32 v151, v151
	s_waitcnt lgkmcnt(4)
	v_mfma_f32_32x32x16_bf16 v[34:49], v[184:187], v[114:117], v[34:49]
	ds_read_b128 v[200:203], v91 offset:16384
	v_exp_f32_e32 v152, v152
	v_exp_f32_e32 v153, v153
	s_waitcnt lgkmcnt(4)
	v_mfma_f32_32x32x16_bf16 v[50:65], v[188:191], v[114:117], v[50:65]
	ds_read_b128 v[204:207], v91 offset:24576
	v_add_f32_e32 v122, v146, v122
	v_add_f32_e32 v122, v147, v122
	v_add_f32_e32 v122, v148, v122
	v_add_f32_e32 v122, v149, v122
	s_waitcnt lgkmcnt(4)
	v_mfma_f32_32x32x16_bf16 v[66:81], v[192:195], v[114:117], v[66:81]
	v_add_f32_e32 v122, v150, v122
	v_add_f32_e32 v122, v151, v122
	v_add_f32_e32 v122, v152, v122
	v_add_f32_e32 v122, v153, v122
	v_cvt_pk_bf16_f32 v118, v146, v147
	v_cvt_pk_bf16_f32 v119, v148, v149
	v_cvt_pk_bf16_f32 v120, v150, v151
	v_cvt_pk_bf16_f32 v121, v152, v153
	s_waitcnt lgkmcnt(3)
	s_nop 0
	v_mfma_f32_32x32x16_bf16 v[18:33], v[196:199], v[118:121], v[18:33]
	ds_read_b128 v[128:131], v92 offset:0
	v_exp_f32_e32 v154, v154
	v_exp_f32_e32 v155, v155
	v_exp_f32_e32 v156, v156
	s_waitcnt lgkmcnt(3)
	v_mfma_f32_32x32x16_bf16 v[34:49], v[216:219], v[118:121], v[34:49]
	ds_read_b128 v[184:187], v92 offset:8192
	v_exp_f32_e32 v157, v157
	v_exp_f32_e32 v158, v158
	v_exp_f32_e32 v159, v159
	s_waitcnt lgkmcnt(3)
	v_mfma_f32_32x32x16_bf16 v[50:65], v[200:203], v[118:121], v[50:65]
	ds_read_b128 v[188:191], v92 offset:16384
	v_exp_f32_e32 v160, v160
	v_exp_f32_e32 v161, v161
	v_add_f32_e32 v122, v154, v122
	v_add_f32_e32 v122, v155, v122
	s_waitcnt lgkmcnt(3)
	v_mfma_f32_32x32x16_bf16 v[66:81], v[204:207], v[118:121], v[66:81]
	ds_read_b128 v[192:195], v92 offset:24576
	v_add_f32_e32 v122, v156, v122
	v_add_f32_e32 v122, v157, v122
	v_add_f32_e32 v122, v158, v122
	v_add_f32_e32 v122, v159, v122
	v_add_f32_e32 v122, v160, v122
	v_add_f32_e32 v122, v161, v122
	v_cvt_pk_bf16_f32 v114, v154, v155
	v_cvt_pk_bf16_f32 v115, v156, v157
	v_cvt_pk_bf16_f32 v116, v158, v159
	v_cvt_pk_bf16_f32 v117, v160, v161
	s_waitcnt lgkmcnt(3)
	s_nop 0
	v_mfma_f32_32x32x16_bf16 v[18:33], v[128:131], v[114:117], v[18:33]
	ds_read_b128 v[196:199], v93 offset:0
	v_exp_f32_e32 v162, v162
	v_exp_f32_e32 v163, v163
	v_exp_f32_e32 v164, v164
	s_waitcnt lgkmcnt(3)
	v_mfma_f32_32x32x16_bf16 v[34:49], v[184:187], v[114:117], v[34:49]
	ds_read_b128 v[216:219], v93 offset:8192
	v_exp_f32_e32 v165, v165
	v_exp_f32_e32 v166, v166
	v_exp_f32_e32 v167, v167
	s_waitcnt lgkmcnt(3)
	v_mfma_f32_32x32x16_bf16 v[50:65], v[188:191], v[114:117], v[50:65]
	ds_read_b128 v[200:203], v93 offset:16384
	v_exp_f32_e32 v168, v168
	v_exp_f32_e32 v169, v169
	v_add_f32_e32 v122, v162, v122
	v_add_f32_e32 v122, v163, v122
	s_waitcnt lgkmcnt(3)
	v_mfma_f32_32x32x16_bf16 v[66:81], v[192:195], v[114:117], v[66:81]
	ds_read_b128 v[204:207], v93 offset:24576
	v_add_f32_e32 v122, v164, v122
	v_add_f32_e32 v122, v165, v122
	v_add_f32_e32 v122, v166, v122
	v_add_f32_e32 v122, v167, v122
	v_add_f32_e32 v122, v168, v122
	v_add_f32_e32 v122, v169, v122
	v_cvt_pk_bf16_f32 v118, v162, v163
	v_cvt_pk_bf16_f32 v119, v164, v165
	v_cvt_pk_bf16_f32 v120, v166, v167
	v_cvt_pk_bf16_f32 v121, v168, v169
	s_waitcnt lgkmcnt(3)
	s_nop 0
	v_mfma_f32_32x32x16_bf16 v[18:33], v[196:199], v[118:121], v[18:33]
	s_waitcnt lgkmcnt(2)
	v_mfma_f32_32x32x16_bf16 v[34:49], v[216:219], v[118:121], v[34:49]
	s_waitcnt lgkmcnt(1)
	v_mfma_f32_32x32x16_bf16 v[50:65], v[200:203], v[118:121], v[50:65]
	s_waitcnt lgkmcnt(0)
	v_mfma_f32_32x32x16_bf16 v[66:81], v[204:207], v[118:121], v[66:81]
	s_waitcnt vmcnt(0)
	s_waitcnt lgkmcnt(0)
	s_barrier
	v_readlane_b32 s64, v175, 0
	v_readlane_b32 s65, v175, 1
	v_readlane_b32 s66, v175, 2
	v_readlane_b32 s67, v175, 3
	v_readlane_b32 s68, v175, 4
	v_readlane_b32 s69, v175, 5
	v_readlane_b32 s70, v175, 6
	v_readlane_b32 s71, v175, 7
	v_readlane_b32 s72, v175, 8
	v_readlane_b32 s73, v175, 9
	v_readlane_b32 s74, v175, 10
	v_readlane_b32 s75, v175, 11
	v_readlane_b32 s76, v175, 12
	v_readlane_b32 s77, v175, 13
	v_readlane_b32 s78, v175, 14
	v_readlane_b32 s79, v175, 15
	s_nop 4
	s_mov_b32 s10, 0x3fb8aa3b
	s_mov_b32 s11, 0xc2ce8ed0
	s_mov_b32 s6, 0x42b17218
	v_cmp_eq_u32_e64 s[40:41], 0, v179
	s_lshl_b32 s30, s14, 1
	v_lshlrev_b32_e32 v196, 3, v178
	v_mov_b32_e32 v197, 0
	v_lshlrev_b32_e32 v198, 4, v179
	v_or3_b32 v198, v198, v177, v180
	v_ashrrev_i32_e32 v199, 31, v198
	v_lshlrev_b64 v[198:199], 11, v[198:199]
	s_mov_b64 s[100:101], 0x18a10000
	v_lshl_add_u64 v[198:199], s[42:43], 0, v[198:199]
	v_lshl_add_u64 v[198:199], v[198:199], 0, s[30:31]
	v_lshl_add_u64 v[198:199], v[198:199], 0, v[196:197]
	v_lshl_add_u64 v[198:199], v[198:199], 0, s[100:101]
	global_load_dwordx2 v[146:147], v[198:199], off
	global_load_dwordx2 v[148:149], v[198:199], off offset:32
	global_load_dwordx2 v[150:151], v[198:199], off offset:64
	global_load_dwordx2 v[152:153], v[198:199], off offset:96
	global_load_dwordx2 v[188:189], v[198:199], off offset:128
	global_load_dwordx2 v[190:191], v[198:199], off offset:160
	global_load_dwordx2 v[192:193], v[198:199], off offset:192
	global_load_dwordx2 v[194:195], v[198:199], off offset:224
	s_mov_b64 s[100:101], exec
	s_and_b64 exec, exec, s[4:5]
	s_cbranch_execz .Lpop_skip
	v_readlane_b32 s14, v255, 22
	v_readlane_b32 s15, v255, 23
	v_mov_b32_e32 v224, 1
	s_nop 4
	global_atomic_add v224, v0, v224, s[14:15] sc0
